# near-diagonal bias via precomputed LDS table (1 ds_read + 1 add per score instead of ~8 VALU)
# speedup vs baseline: 1.0180x; 1.0133x over previous
; __device__ __forceinline__ int t5_bucket(int d){ if(d<16)return d; int b=16+(int)(__builtin_log2f((float)d*(1.0f/16.0f))*(16.0f/3.0f)); return b>31?31:b; }
; template<int THRL> __device__ __forceinline__ void attn_unit(int b,int h,int qb,const AttnArgs&A,char*shm,bool setup){
;     ...
;   if(setup){
;     if(tid<256){ const int m_=tid>>7,d=tid&127; biasT[tid]=A.relb[t5_bucket(d)*16+2*h+m_]*LOG2E; }
;     else if(tid<384){ subgT[tid-256]=A.subg[tid-256]*A.onem; }
;     asm volatile("s_waitcnt vmcnt(0) lgkmcnt(0)\n\ts_barrier":::"memory");
;   }
;     ...
;       if(!far){ const float*bt=biasT+mp*128; const int dq=qpos-kv0-4*hi;
;         #pragma unroll
;         for(int r=0;r<16;++r){ const int d=dq-((r&3)+8*(r>>2));
;           const int i0=d<0?0:(d>127?127:d);
;           const float b0=bt[i0];
;           const float n0=d>=0?0.f:-INFINITY;
;           p0[r]=(p0[r]+(b0-cfar))+n0; if((r&7)==7)asm volatile("":::"memory"); }
;         #pragma unroll
;         for(int r=0;r<16;++r){ const int d1=dq-32-((r&3)+8*(r>>2));
;           const int i1=d1<0?0:(d1>127?127:d1);
;           const float b1=bt[i1];
;           const float n1=d1>=0?0.f:-INFINITY;
;           p1[r]=(p1[r]+(b1-cfar))+n1; if((r&7)==7)asm volatile("":::"memory"); } }
.LBB0_234:
	s_or_b64 exec, exec, s[8:9]
	s_waitcnt vmcnt(0) lgkmcnt(0)
	s_barrier
	v_and_b32_e32 v0, 0xff, v2
	v_subrev_u32_e32 v3, 63, v0
	v_med3_i32 v4, v3, 0, v240
	v_lshrrev_b32_e32 v5, 8, v2
	v_lshl_add_u32 v4, v5, 7, v4
	v_lshlrev_b32_e32 v4, 2, v4
	v_lshlrev_b32_e32 v5, 9, v5
	v_add_u32_e32 v4, 0x18800, v4
	v_add_u32_e32 v5, 0x18800, v5
	ds_read_b32 v4, v4
	ds_read_b32 v5, v5 offset:508
	v_cmp_gt_i32_e32 vcc, 0, v3
	v_lshlrev_b32_e32 v0, 2, v2
	v_add_u32_e32 v0, 0x1d000, v0
	s_waitcnt lgkmcnt(0)
	v_sub_f32_e32 v4, v4, v5
	s_nop 1
	v_cndmask_b32_e32 v4, v4, v241, vcc
	ds_write_b32 v0, v4

; #define SBAR() __builtin_amdgcn_sched_barrier(0)
; template<int THRL> __device__ __forceinline__ void attn_unit(int b,int h,int qb,const AttnArgs&A,char*shm,bool setup){
;     ...
;   bf16x8 qr[4];
;   #pragma unroll
;   for(int d0=0;d0<4;++d0)qr[d0]=*reinterpret_cast<const bf16x8*>(&Qw[(long)r32*PITCH+d0*16+hi*8]);
;   DMA_K(0,0); DMA_V(0,0); DMA_K(1,SLOT16);
;   DMA_V(1,SLOT16); { const unsigned char*g_=imgS+((size_t)(NT>2?2:NT-1)<<15); const unsigned d_=(unsigned)__builtin_amdgcn_readfirstlane(NT>2?kdst+2*SLOT16:ddst); glds16s(g_,voff,d_); glds16s(g_+8192,voff,d_+8192); }
;   float mhat=0.f,l=0.f;
;   f32x16 o[4];
;   #pragma unroll
;   for(int d0=0;d0<4;++d0)o[d0]=f32x16{};
;   const int qpos=qw0+r32;
;   f32x16 p0,p1; u32x4 pw[4]; bf16x8 kf[8]; bf16x8 va[4],vb[4];
;   f32x16 cini;
;   #pragma unroll
;   for(int r=0;r<16;++r)cini[r]=cfar;
;   asm volatile("":"+v"(cini));
;     ...
;   WAIT_BAR(8);
;   KRD(kp0);
;   int ks_t=0,ks_n=SLOT16,vs_t=0,vs_nn=2*SLOT16;
;   for(int t=0;t<NT;++t){
;     WAIT_BAR(4);
;     const int kv0=t*KVBLK;
;     const bool act=(kv0<=qw0+QBLK-1);
;     const bool actn=(t+1<NT)&&(kv0+KVBLK<=qw0+QBLK-1);
;     const lds_cptr vp=vp0+vs_t;
;     const bool dk=(t+3<NT), dv=(t+2<NT);
;     const unsigned char*gk_=imgS+((size_t)(dk?t+3:NT-1)<<15); const unsigned char*gv_=imgS+((size_t)(dv?t+2:NT-1)<<15)+16384;
;     const unsigned kd_=(unsigned)__builtin_amdgcn_readfirstlane(dk?kdst+ks_t:ddst), vd_=(unsigned)__builtin_amdgcn_readfirstlane(dv?vdst+vs_nn:ddst);
;     if(act){
;       VRK(va,vp,0); VRK(vb,vp,1);
;       SBAR();
;       QKM(cini);
;     }
;     if(act){
;       const bool far=(qw0-(kv0+63)>=113);
;       if(!far){ const float*bt=biasT+mp*128; const int dq=qpos-kv0-4*hi;
;         #pragma unroll
;         for(int r=0;r<16;++r){ const int d=dq-((r&3)+8*(r>>2));
;           const int i0=d<0?0:(d>127?127:d);
;           const float b0=bt[i0];
;           const float n0=d>=0?0.f:-INFINITY;
;           p0[r]=(p0[r]+(b0-cfar))+n0; if((r&7)==7)asm volatile("":::"memory"); }
;         #pragma unroll
;         for(int r=0;r<16;++r){ const int d1=dq-32-((r&3)+8*(r>>2));
;           const int i1=d1<0?0:(d1>127?127:d1);
;           const float b1=bt[i1];
;           const float n1=d1>=0?0.f:-INFINITY;
;           p1[r]=(p1[r]+(b1-cfar))+n1; if((r&7)==7)asm volatile("":::"memory"); } }
.Lprio_skip:
	global_load_dwordx4 v[130:133], v0, s[8:9]
	global_load_dwordx4 v[134:137], v0, s[8:9] offset:32
	global_load_dwordx4 v[138:141], v0, s[8:9] offset:64
	global_load_dwordx4 v[142:145], v0, s[8:9] offset:96
	s_lshl_b32 s8, s47, 9
	s_add_i32 s29, s8, 0
	s_lshl_b32 s41, s20, 10
	s_add_i32 s29, s29, 0x18800
	s_cmp_lg_u32 0, -1
	s_cselect_b32 s8, 0, 0
	v_and_b32_e32 v207, 63, v2
	v_mov_b32_e32 v0, s29
	s_add_i32 s46, s41, s8
	s_add_i32 s8, s22, 0x80
	v_lshl_or_b32 v209, v207, 4, s41
	s_waitcnt vmcnt(19)
	ds_read_b32 v64, v0 offset:508
	s_ashr_i32 s72, s8, 6
	s_mov_b32 s8, m0
	s_mov_b32 m0, s46
	s_nop 0
	global_load_lds_dwordx4 v209, s[42:43]
	s_mov_b32 m0, s8
	s_add_i32 s8, s46, 0x2000
	s_mov_b32 s9, m0
	s_mov_b32 m0, s8
	s_nop 0
	global_load_lds_dwordx4 v209, s[30:31]
	s_mov_b32 m0, s9
	s_add_i32 s99, s46, 0xc000
	s_mov_b32 s8, m0
	s_mov_b32 m0, s99
	s_nop 0
	global_load_lds_dwordx4 v209, s[34:35]
	s_mov_b32 m0, s8
	s_add_i32 s8, s46, 0xe000
	s_mov_b32 s9, m0
	s_mov_b32 m0, s8
	s_nop 0
	global_load_lds_dwordx4 v209, s[92:93]
	s_mov_b32 m0, s9
	s_add_i32 s8, s46, 0x4000
	s_mov_b32 s9, m0
	s_mov_b32 m0, s8
	s_nop 0
	global_load_lds_dwordx4 v209, s[96:97]
	s_mov_b32 m0, s9
	s_add_i32 s8, s46, 0x6000
	s_mov_b32 s9, m0
	s_mov_b32 m0, s8
	s_nop 0
	global_load_lds_dwordx4 v209, s[4:5]
	s_mov_b32 m0, s9
	s_add_i32 s8, s46, 0x10000
	s_mov_b32 s9, m0
	s_mov_b32 m0, s8
	s_nop 0
	global_load_lds_dwordx4 v209, s[6:7]
	s_mov_b32 m0, s9
	s_add_i32 s8, s46, 0x12000
	s_add_i32 s81, s72, -1
	s_mov_b32 s9, m0
	s_mov_b32 m0, s8
	s_nop 0
	global_load_lds_dwordx4 v209, s[12:13]
	s_mov_b32 m0, s9
	s_min_i32 s8, s81, 2
	s_ashr_i32 s9, s8, 31
	s_add_i32 s98, s46, 0x19000
	s_lshl_b64 s[8:9], s[8:9], 15
	s_add_u32 s8, s42, s8
	s_addc_u32 s9, s43, s9
	s_add_i32 s20, s46, 0x8000
	s_cmp_gt_i32 s72, 2
	s_cselect_b64 vcc, -1, 0
	s_waitcnt lgkmcnt(0)
	v_mov_b32_e32 v78, v64
	v_mov_b32_e32 v79, v64
	s_and_b64 s[82:83], vcc, exec
	v_mov_b32_e32 v65, v64
	v_mov_b32_e32 v66, v64
	v_mov_b32_e32 v67, v64
	v_mov_b32_e32 v68, v64
	v_mov_b32_e32 v69, v64
	v_mov_b32_e32 v70, v64
	v_mov_b32_e32 v71, v64
	v_mov_b32_e32 v72, v64
	v_mov_b32_e32 v73, v64
	v_mov_b32_e32 v74, v64
	v_mov_b32_e32 v75, v64
	v_mov_b32_e32 v76, v64
	v_mov_b32_e32 v77, v64
	s_waitcnt vmcnt(9)
	v_mov_b64_e32 v[112:113], v[78:79]
	s_cselect_b32 s20, s20, s98
	s_mov_b32 s21, m0
	s_mov_b32 m0, s20
	s_nop 0
	global_load_lds_dwordx4 v209, s[8:9]
	s_mov_b32 m0, s21
	s_add_u32 s82, s8, 0x2000
	v_mov_b64_e32 v[110:111], v[76:77]
	v_mov_b64_e32 v[108:109], v[74:75]
	v_mov_b64_e32 v[106:107], v[72:73]
	v_mov_b64_e32 v[104:105], v[70:71]
	v_mov_b64_e32 v[102:103], v[68:69]
	v_mov_b64_e32 v[100:101], v[66:67]
	v_mov_b64_e32 v[98:99], v[64:65]
	s_addc_u32 s83, s9, 0
	s_addk_i32 s20, 0x2000
	s_mov_b32 s21, m0
	s_mov_b32 m0, s20
	s_nop 0
	global_load_lds_dwordx4 v209, s[82:83]
	s_mov_b32 m0, s21
	s_waitcnt vmcnt(8) lgkmcnt(0)
	s_barrier
	s_cmp_lt_i32 s72, 1
	s_cbranch_scc1 .LBB0_251
	s_lshl_b32 s20, s47, 13
	v_lshlrev_b32_e32 v0, 10, v206
	v_lshlrev_b32_e32 v2, 4, v208
	s_add_i32 s20, s20, 0
	v_add3_u32 v65, s20, v0, v2
	ds_read_b128 v[114:117], v65
	ds_read_b128 v[118:121], v65 offset:512
	ds_read_b128 v[122:125], v65 offset:2048
	ds_read_b128 v[126:129], v65 offset:2560
	ds_read_b128 v[146:149], v65 offset:4096
	ds_read_b128 v[150:153], v65 offset:4608
	ds_read_b128 v[154:157], v65 offset:6144
	ds_read_b128 v[158:161], v65 offset:6656
	s_cmp_gt_u32 s72, 3
	s_cselect_b32 s82, s46, s98
	s_cmp_lg_u32 0, -1
	s_cselect_b32 s20, 0, 0
	s_add_i32 s20, s20, s41
	s_waitcnt vmcnt(4) lgkmcnt(0)
	s_barrier
	s_add_i32 s20, s20, 0x14000
	v_lshlrev_b32_e32 v3, 9, v206
	s_and_b64 s[94:95], vcc, exec
	v_add3_u32 v210, 0, v3, v2
	v_lshlrev_b32_e32 v212, 2, v206
	s_cselect_b32 s73, s20, s98
	s_cmp_gt_i32 s22, -1
	s_mov_b64 vcc, -1
	s_cbranch_scc0 .LBB0_240
	ds_read_b128 v[42:45], v210 offset:49152
	ds_read_b128 v[174:177], v210 offset:50176
	ds_read_b128 v[38:41], v210 offset:53248
	ds_read_b128 v[170:173], v210 offset:54272
	ds_read_b128 v[34:37], v210 offset:57344
	ds_read_b128 v[166:169], v210 offset:58368
	ds_read_b128 v[178:181], v210 offset:61440
	ds_read_b128 v[162:165], v210 offset:62464
	s_sub_i32 s20, s40, 63
	s_waitcnt lgkmcnt(14)
	v_mfma_f32_32x32x16_bf16 v[18:33], v[114:117], v[130:133], v[98:113]
	s_cmpk_gt_i32 s20, 0x70
	v_mfma_f32_32x32x16_bf16 v[2:17], v[118:121], v[130:133], v[98:113]
	s_waitcnt lgkmcnt(12)
	v_mfma_f32_32x32x16_bf16 v[2:17], v[126:129], v[134:137], v[2:17]
	v_mfma_f32_32x32x16_bf16 v[18:33], v[122:125], v[134:137], v[18:33]
	s_waitcnt lgkmcnt(10)
	v_mfma_f32_32x32x16_bf16 v[2:17], v[150:153], v[138:141], v[2:17]
	v_mfma_f32_32x32x16_bf16 v[18:33], v[146:149], v[138:141], v[18:33]
	s_waitcnt lgkmcnt(8)
	v_mfma_f32_32x32x16_bf16 v[2:17], v[158:161], v[142:145], v[2:17]
	v_mfma_f32_32x32x16_bf16 v[18:33], v[154:157], v[142:145], v[18:33]
	s_cbranch_scc1 .LBB0_239
	v_or_b32_e32 v0, s40, v208
	v_sub_u32_e32 v0, v0, v212
	s_sub_i32 s20, s29, 0x18800
	s_lshl_b32 s20, s20, 1
	s_add_i32 s20, s20, 0x1d000
	v_lshl_add_u32 v82, v0, 2, s20
	ds_read_b32 v46, v82 offset:252
	ds_read_b32 v47, v82 offset:248
	ds_read_b32 v48, v82 offset:244
	ds_read_b32 v49, v82 offset:240
	ds_read_b32 v50, v82 offset:220
	ds_read_b32 v51, v82 offset:216
	ds_read_b32 v52, v82 offset:212
	ds_read_b32 v53, v82 offset:208
	ds_read_b32 v54, v82 offset:188
	ds_read_b32 v55, v82 offset:184
	ds_read_b32 v56, v82 offset:180
	ds_read_b32 v57, v82 offset:176
	ds_read_b32 v58, v82 offset:156
	ds_read_b32 v59, v82 offset:152
	ds_read_b32 v60, v82 offset:148
	ds_read_b32 v61, v82 offset:144
	ds_read_b32 v66, v82 offset:124
	ds_read_b32 v67, v82 offset:120
	ds_read_b32 v68, v82 offset:116
	ds_read_b32 v69, v82 offset:112
	ds_read_b32 v70, v82 offset:92
	ds_read_b32 v71, v82 offset:88
	ds_read_b32 v72, v82 offset:84
	ds_read_b32 v73, v82 offset:80
	ds_read_b32 v74, v82 offset:60
	ds_read_b32 v75, v82 offset:56
	ds_read_b32 v76, v82 offset:52
	ds_read_b32 v77, v82 offset:48
	ds_read_b32 v78, v82 offset:28
	ds_read_b32 v79, v82 offset:24
	ds_read_b32 v80, v82 offset:20
	ds_read_b32 v81, v82 offset:16
	s_waitcnt lgkmcnt(14)
	v_pk_add_f32 v[18:19], v[18:19], v[46:47]
	v_pk_add_f32 v[20:21], v[20:21], v[48:49]
	v_pk_add_f32 v[22:23], v[22:23], v[50:51]
	v_pk_add_f32 v[24:25], v[24:25], v[52:53]
	v_pk_add_f32 v[26:27], v[26:27], v[54:55]
	v_pk_add_f32 v[28:29], v[28:29], v[56:57]
	v_pk_add_f32 v[30:31], v[30:31], v[58:59]
	v_pk_add_f32 v[32:33], v[32:33], v[60:61]
	s_waitcnt lgkmcnt(0)
	v_pk_add_f32 v[2:3], v[2:3], v[66:67]
	v_pk_add_f32 v[4:5], v[4:5], v[68:69]
	v_pk_add_f32 v[6:7], v[6:7], v[70:71]
	v_pk_add_f32 v[8:9], v[8:9], v[72:73]
	v_pk_add_f32 v[10:11], v[10:11], v[74:75]
	v_pk_add_f32 v[12:13], v[12:13], v[76:77]
	v_pk_add_f32 v[14:15], v[14:15], v[78:79]
	v_pk_add_f32 v[16:17], v[16:17], v[80:81]

; #define SBAR() __builtin_amdgcn_sched_barrier(0)
; #define WAIT_BAR(N) asm volatile("s_waitcnt vmcnt(" #N ") lgkmcnt(0)\n\ts_barrier":::"memory")
;   #define VRK(dst,vp_,ks_) do{ _Pragma("unroll") for(int d0_=0;d0_<4;++d0_){ dst[d0_]=*(const __attribute__((address_space(3))) bf16x8*)((vp_)+d0_*4096+(ks_)*1024); } }while(0)
; template<int THRL> __device__ __forceinline__ void attn_unit(int b,int h,int qb,const AttnArgs&A,char*shm,bool setup){
;     ...
;     WAIT_BAR(4);
;     const int kv0=t*KVBLK;
;     const bool act=(kv0<=qw0+QBLK-1);
;     const bool actn=(t+1<NT)&&(kv0+KVBLK<=qw0+QBLK-1);
;     const lds_cptr vp=vp0+vs_t;
;     const bool dk=(t+3<NT), dv=(t+2<NT);
;     const unsigned char*gk_=imgS+((size_t)(dk?t+3:NT-1)<<15); const unsigned char*gv_=imgS+((size_t)(dv?t+2:NT-1)<<15)+16384;
;     const unsigned kd_=(unsigned)__builtin_amdgcn_readfirstlane(dk?kdst+ks_t:ddst), vd_=(unsigned)__builtin_amdgcn_readfirstlane(dv?vdst+vs_nn:ddst);
;     if(act){
;       VRK(va,vp,0); VRK(vb,vp,1);
;       SBAR();
;       QKM(cini);
;     }
;     if(act){
;       const bool far=(qw0-(kv0+63)>=113);
;       if(!far){ const float*bt=biasT+mp*128; const int dq=qpos-kv0-4*hi;
;         #pragma unroll
;         for(int r=0;r<16;++r){ const int d=dq-((r&3)+8*(r>>2));
;           const int i0=d<0?0:(d>127?127:d);
;           const float b0=bt[i0];
;           const float n0=d>=0?0.f:-INFINITY;
;           p0[r]=(p0[r]+(b0-cfar))+n0; if((r&7)==7)asm volatile("":::"memory"); }
;         #pragma unroll
;         for(int r=0;r<16;++r){ const int d1=dq-32-((r&3)+8*(r>>2));
;           const int i1=d1<0?0:(d1>127?127:d1);
;           const float b1=bt[i1];
;           const float n1=d1>=0?0.f:-INFINITY;
;           p1[r]=(p1[r]+(b1-cfar))+n1; if((r&7)==7)asm volatile("":::"memory"); } }
.LBB0_243:
	s_add_i32 s95, s41, 1
	s_add_i32 s20, s73, s46
	s_cmp_lt_i32 s95, s72
	s_cselect_b32 s82, s20, s98
	s_add_i32 s20, s9, s99
	s_waitcnt vmcnt(4) lgkmcnt(0)
	s_barrier
	s_cmp_lt_i32 s41, s72
	s_cselect_b32 s73, s20, s98
	s_cmp_gt_i32 s40, s80
	s_cbranch_scc1 .LBB0_249
	v_add_u32_e32 v15, s94, v210
	ds_read_b128 v[162:165], v15 offset:49152
	s_waitcnt lgkmcnt(4)
	ds_read_b128 v[146:149], v15 offset:50176
	s_waitcnt lgkmcnt(2)
	ds_read_b128 v[158:161], v15 offset:53248
	ds_read_b128 v[10:13], v15 offset:54272
	ds_read_b128 v[154:157], v15 offset:57344
	ds_read_b128 v[6:9], v15 offset:58368
	ds_read_b128 v[150:153], v15 offset:61440
	ds_read_b128 v[2:5], v15 offset:62464
	v_mfma_f32_32x32x16_bf16 v[114:129], v[178:181], v[130:133], v[82:97]
	s_cmpk_gt_i32 s22, 0x70
	v_mfma_f32_32x32x16_bf16 v[98:113], v[182:185], v[130:133], v[82:97]
	v_mfma_f32_32x32x16_bf16 v[98:113], v[186:189], v[134:137], v[98:113]
	v_mfma_f32_32x32x16_bf16 v[114:129], v[166:169], v[134:137], v[114:129]
	v_mfma_f32_32x32x16_bf16 v[98:113], v[190:193], v[138:141], v[98:113]
	v_mfma_f32_32x32x16_bf16 v[114:129], v[174:177], v[138:141], v[114:129]
	v_mfma_f32_32x32x16_bf16 v[98:113], v[194:197], v[142:145], v[98:113]
	v_mfma_f32_32x32x16_bf16 v[114:129], v[170:173], v[142:145], v[114:129]
	s_cbranch_scc1 .LBB0_246
	v_add_u32_e32 v212, s22, v14
	s_sub_i32 s20, s29, 0x18800
	s_lshl_b32 s20, s20, 1
	s_add_i32 s20, s20, 0x1d000
	v_lshl_add_u32 v213, v212, 2, s20
	ds_read_b32 v166, v213 offset:504
	ds_read_b32 v167, v213 offset:500
	ds_read_b32 v168, v213 offset:496
	ds_read_b32 v169, v213 offset:492
	ds_read_b32 v170, v213 offset:472
	ds_read_b32 v171, v213 offset:468
	ds_read_b32 v172, v213 offset:464
	ds_read_b32 v173, v213 offset:460
	ds_read_b32 v174, v213 offset:440
	ds_read_b32 v175, v213 offset:436
	ds_read_b32 v176, v213 offset:432
	ds_read_b32 v177, v213 offset:428
	ds_read_b32 v178, v213 offset:408
	ds_read_b32 v179, v213 offset:404
	ds_read_b32 v180, v213 offset:400
	ds_read_b32 v181, v213 offset:396
	ds_read_b32 v182, v213 offset:376
	ds_read_b32 v183, v213 offset:372
	ds_read_b32 v184, v213 offset:368
	ds_read_b32 v185, v213 offset:364
	ds_read_b32 v186, v213 offset:344
	ds_read_b32 v187, v213 offset:340
	ds_read_b32 v188, v213 offset:336
	ds_read_b32 v189, v213 offset:332
	ds_read_b32 v190, v213 offset:312
	ds_read_b32 v191, v213 offset:308
	ds_read_b32 v192, v213 offset:304
	ds_read_b32 v193, v213 offset:300
	ds_read_b32 v194, v213 offset:280
	ds_read_b32 v195, v213 offset:276
	ds_read_b32 v196, v213 offset:272
	ds_read_b32 v197, v213 offset:268
	s_waitcnt lgkmcnt(14)
	v_pk_add_f32 v[114:115], v[114:115], v[166:167]
	v_pk_add_f32 v[116:117], v[116:117], v[168:169]
	v_pk_add_f32 v[118:119], v[118:119], v[170:171]
	v_pk_add_f32 v[120:121], v[120:121], v[172:173]
	v_pk_add_f32 v[122:123], v[122:123], v[174:175]
	v_pk_add_f32 v[124:125], v[124:125], v[176:177]
	v_pk_add_f32 v[126:127], v[126:127], v[178:179]
	v_pk_add_f32 v[128:129], v[128:129], v[180:181]
	s_waitcnt lgkmcnt(0)
	v_pk_add_f32 v[98:99], v[98:99], v[182:183]
	v_pk_add_f32 v[100:101], v[100:101], v[184:185]
	v_pk_add_f32 v[102:103], v[102:103], v[186:187]
	v_pk_add_f32 v[104:105], v[104:105], v[188:189]
	v_pk_add_f32 v[106:107], v[106:107], v[190:191]
	v_pk_add_f32 v[108:109], v[108:109], v[192:193]
	v_pk_add_f32 v[110:111], v[110:111], v[194:195]
	v_pk_add_f32 v[112:113], v[112:113], v[196:197]
